# v043 stack + PD scans rewritten: 64-lane S5 scan with deep load ring, GLA state scan software-pipelined in 3 batches of 11 with scalar index math
# speedup vs baseline: 1.0087x; 1.0054x over previous
.LBB0_1268:
	s_andn2_b64 vcc, exec, s[14:15]
	s_cbranch_vccnz .LBB0_1331
	v_mov_b32_e32 v2, v0
	v_readlane_b32 s4, v253, 20
	s_nop 0
	v_cmp_gt_i32_e32 vcc, 32, v2
	v_add_u32_e32 v140, s4, v2
	s_movk_i32 s4, 0x2000
	v_cmp_gt_i32_e64 s[40:41], s4, v140
	s_and_b64 s[4:5], vcc, s[40:41]
	s_and_saveexec_b64 s[18:19], s[4:5]
	s_cbranch_execz .LBB0_1276
	s_mov_b64 exec, -1
	v_readlane_b32 s4, v253, 20
	v_mbcnt_lo_u32_b32 v4, -1, 0
	v_mbcnt_hi_u32_b32 v4, -1, v4
	v_readlane_b32 s34, v250, 23
	v_readlane_b32 s35, v250, 24
	v_and_b32_e32 v5, 31, v4
	v_lshrrev_b32_e32 v6, 5, v4
	v_add_u32_e32 v7, s4, v5
	v_readlane_b32 s4, v252, 62
	v_readlane_b32 s5, v252, 63
	v_readlane_b32 s6, v253, 2
	v_readlane_b32 s7, v253, 3
	v_and_b32_e32 v8, 63, v7
	v_bfe_u32 v9, v7, 6, 5
	v_bfe_u32 v10, v7, 11, 1
	v_lshrrev_b32_e32 v11, 12, v7
	v_and_b32_e32 v25, 0xfff, v7
	v_lshlrev_b32_e32 v25, 3, v25
	s_mov_b32 s40, 0
	s_mov_b32 s41, -1
	global_load_dwordx2 v[12:13], v25, s[34:35]
	v_lshlrev_b32_e32 v34, 10, v9
	v_lshl_add_u32 v31, v10, 8, v34
	v_lshl_add_u32 v34, v10, 9, v34
	v_lshl_add_u32 v34, v8, 2, v34
	v_lshl_add_u32 v31, v8, 1, v31
	v_lshl_add_u32 v34, v6, 8, v34
	v_lshl_add_u32 v31, v6, 7, v31
	v_add_u32_e32 v31, 0x200, v31
	v_mov_b32_e32 v35, 0
	v_cmp_eq_u32_e32 vcc, 0, v10
	v_mov_b32_e32 v24, 0xffff8000
	v_mov_b32_e32 v27, 0x8000
	v_cndmask_b32_e32 v24, v24, v27, vcc
	v_ashrrev_i32_e32 v25, 31, v24
	v_lshlrev_b32_e32 v26, 4, v11
	v_add_u32_e32 v26, 0x400, v26
	v_mul_u32_u24_e32 v27, 15, v10
	v_add_u32_e32 v26, v26, v27
	v_lshlrev_b32_e32 v26, 15, v26
	v_lshlrev_b32_e32 v29, 9, v11
	v_mul_u32_u24_e32 v27, 0x1ff, v10
	v_add_u32_e32 v29, v29, v27
	v_lshlrev_b32_e32 v29, 15, v29
	v_add_u32_e32 v30, v31, v29
	v_add_u32_e32 v31, v31, v26
	v_lshl_add_u64 v[18:19], s[4:5], 0, v[34:35]
	v_mov_b32_e32 v27, 0
	v_mov_b32_e32 v36, v29
	v_mov_b32_e32 v37, 0
	v_lshl_add_u64 v[32:33], v[18:19], 0, v[36:37]
	v_mov_b32_e32 v36, v26
	v_lshl_add_u64 v[18:19], v[18:19], 0, v[36:37]
	v_mov_b32_e32 v20, 0
	v_mov_b32_e32 v21, 0
	global_load_dword v40, v[18:19], off
	v_lshl_add_u64 v[18:19], v[18:19], 0, v[24:25]
	global_load_dword v42, v[18:19], off
	v_lshl_add_u64 v[18:19], v[18:19], 0, v[24:25]
	global_load_dword v44, v[18:19], off
	v_lshl_add_u64 v[18:19], v[18:19], 0, v[24:25]
	global_load_dword v46, v[18:19], off
	v_lshl_add_u64 v[18:19], v[18:19], 0, v[24:25]
	global_load_dword v48, v[18:19], off
	v_lshl_add_u64 v[18:19], v[18:19], 0, v[24:25]
	global_load_dword v50, v[18:19], off
	v_lshl_add_u64 v[18:19], v[18:19], 0, v[24:25]
	global_load_dword v52, v[18:19], off
	v_lshl_add_u64 v[18:19], v[18:19], 0, v[24:25]
	global_load_dword v54, v[18:19], off
	v_lshl_add_u64 v[18:19], v[18:19], 0, v[24:25]
	global_load_dword v56, v[18:19], off
	v_lshl_add_u64 v[18:19], v[18:19], 0, v[24:25]
	global_load_dword v58, v[18:19], off
	v_lshl_add_u64 v[18:19], v[18:19], 0, v[24:25]
	global_load_dword v60, v[18:19], off
	v_lshl_add_u64 v[18:19], v[18:19], 0, v[24:25]
	global_load_dword v62, v[18:19], off
	v_lshl_add_u64 v[18:19], v[18:19], 0, v[24:25]
	global_load_dword v64, v[18:19], off
	v_lshl_add_u64 v[18:19], v[18:19], 0, v[24:25]
	global_load_dword v66, v[18:19], off
	v_lshl_add_u64 v[18:19], v[18:19], 0, v[24:25]
	global_load_dword v68, v[18:19], off
	v_lshl_add_u64 v[18:19], v[18:19], 0, v[24:25]
	global_load_dword v70, v[18:19], off
	v_lshl_add_u64 v[18:19], v[18:19], 0, v[24:25]
	v_mov_b64_e32 v[18:19], v[32:33]
	global_load_dword v72, v[18:19], off
	v_lshl_add_u64 v[18:19], v[18:19], 0, v[24:25]
	global_load_dword v74, v[18:19], off
	v_lshl_add_u64 v[18:19], v[18:19], 0, v[24:25]
	global_load_dword v76, v[18:19], off
	v_lshl_add_u64 v[18:19], v[18:19], 0, v[24:25]
	global_load_dword v78, v[18:19], off
	v_lshl_add_u64 v[18:19], v[18:19], 0, v[24:25]
	global_load_dword v80, v[18:19], off
	v_lshl_add_u64 v[18:19], v[18:19], 0, v[24:25]
	global_load_dword v82, v[18:19], off
	v_lshl_add_u64 v[18:19], v[18:19], 0, v[24:25]
	global_load_dword v84, v[18:19], off
	v_lshl_add_u64 v[18:19], v[18:19], 0, v[24:25]
	global_load_dword v86, v[18:19], off
	v_lshl_add_u64 v[18:19], v[18:19], 0, v[24:25]
	global_load_dword v88, v[18:19], off
	v_lshl_add_u64 v[18:19], v[18:19], 0, v[24:25]
	global_load_dword v90, v[18:19], off
	v_lshl_add_u64 v[18:19], v[18:19], 0, v[24:25]
	global_load_dword v92, v[18:19], off
	v_lshl_add_u64 v[18:19], v[18:19], 0, v[24:25]
	global_load_dword v94, v[18:19], off
	v_lshl_add_u64 v[18:19], v[18:19], 0, v[24:25]
	global_load_dword v96, v[18:19], off
	v_lshl_add_u64 v[18:19], v[18:19], 0, v[24:25]
	global_load_dword v98, v[18:19], off
	v_lshl_add_u64 v[18:19], v[18:19], 0, v[24:25]
	global_load_dword v100, v[18:19], off
	v_lshl_add_u64 v[18:19], v[18:19], 0, v[24:25]
	global_load_dword v102, v[18:19], off
	v_lshl_add_u64 v[18:19], v[18:19], 0, v[24:25]
	s_waitcnt vmcnt(31)
	v_mov_b32_e32 v14, v12
	v_mov_b32_e32 v15, v12
	v_mov_b32_e32 v16, v13
	v_mov_b32_e32 v17, v13
	v_cndmask_b32_e64 v28, v20, v21, s[40:41]
	v_mov_b32_e32 v41, v40
	v_cvt_f16_f32_e32 v28, v28
	v_pk_mul_f32 v[22:23], v[16:17], v[20:21] op_sel:[0,1] op_sel_hi:[1,0]
	v_permlane32_swap_b32_e32 v40, v41
	global_store_short v31, v28, s[6:7]
	v_pk_fma_f32 v[22:23], v[14:15], v[20:21], v[22:23] neg_lo:[0,0,1]
	v_add_u32_e32 v31, v31, v24
	v_pk_add_f32 v[20:21], v[22:23], v[40:41]
	global_load_dword v40, v[18:19], off
	v_lshl_add_u64 v[18:19], v[18:19], 0, v[24:25]
	s_waitcnt vmcnt(32)
	v_cndmask_b32_e64 v28, v20, v21, s[40:41]
	v_mov_b32_e32 v43, v42
	v_cvt_f16_f32_e32 v28, v28
	v_pk_mul_f32 v[22:23], v[16:17], v[20:21] op_sel:[0,1] op_sel_hi:[1,0]
	v_permlane32_swap_b32_e32 v42, v43
	global_store_short v31, v28, s[6:7]
	v_pk_fma_f32 v[22:23], v[14:15], v[20:21], v[22:23] neg_lo:[0,0,1]
	v_add_u32_e32 v31, v31, v24
	v_pk_add_f32 v[20:21], v[22:23], v[42:43]
	global_load_dword v42, v[18:19], off
	v_lshl_add_u64 v[18:19], v[18:19], 0, v[24:25]
	s_waitcnt vmcnt(33)
	v_cndmask_b32_e64 v28, v20, v21, s[40:41]
	v_mov_b32_e32 v45, v44
	v_cvt_f16_f32_e32 v28, v28
	v_pk_mul_f32 v[22:23], v[16:17], v[20:21] op_sel:[0,1] op_sel_hi:[1,0]
	v_permlane32_swap_b32_e32 v44, v45
	global_store_short v31, v28, s[6:7]
	v_pk_fma_f32 v[22:23], v[14:15], v[20:21], v[22:23] neg_lo:[0,0,1]
	v_add_u32_e32 v31, v31, v24
	v_pk_add_f32 v[20:21], v[22:23], v[44:45]
	global_load_dword v44, v[18:19], off
	v_lshl_add_u64 v[18:19], v[18:19], 0, v[24:25]
	s_waitcnt vmcnt(34)
	v_cndmask_b32_e64 v28, v20, v21, s[40:41]
	v_mov_b32_e32 v47, v46
	v_cvt_f16_f32_e32 v28, v28
	v_pk_mul_f32 v[22:23], v[16:17], v[20:21] op_sel:[0,1] op_sel_hi:[1,0]
	v_permlane32_swap_b32_e32 v46, v47
	global_store_short v31, v28, s[6:7]
	v_pk_fma_f32 v[22:23], v[14:15], v[20:21], v[22:23] neg_lo:[0,0,1]
	v_add_u32_e32 v31, v31, v24
	v_pk_add_f32 v[20:21], v[22:23], v[46:47]
	global_load_dword v46, v[18:19], off
	v_lshl_add_u64 v[18:19], v[18:19], 0, v[24:25]
	s_waitcnt vmcnt(35)
	v_cndmask_b32_e64 v28, v20, v21, s[40:41]
	v_mov_b32_e32 v49, v48
	v_cvt_f16_f32_e32 v28, v28
	v_pk_mul_f32 v[22:23], v[16:17], v[20:21] op_sel:[0,1] op_sel_hi:[1,0]
	v_permlane32_swap_b32_e32 v48, v49
	global_store_short v31, v28, s[6:7]
	v_pk_fma_f32 v[22:23], v[14:15], v[20:21], v[22:23] neg_lo:[0,0,1]
	v_add_u32_e32 v31, v31, v24
	v_pk_add_f32 v[20:21], v[22:23], v[48:49]
	global_load_dword v48, v[18:19], off
	v_lshl_add_u64 v[18:19], v[18:19], 0, v[24:25]
	s_waitcnt vmcnt(36)
	v_cndmask_b32_e64 v28, v20, v21, s[40:41]
	v_mov_b32_e32 v51, v50
	v_cvt_f16_f32_e32 v28, v28
	v_pk_mul_f32 v[22:23], v[16:17], v[20:21] op_sel:[0,1] op_sel_hi:[1,0]
	v_permlane32_swap_b32_e32 v50, v51
	global_store_short v31, v28, s[6:7]
	v_pk_fma_f32 v[22:23], v[14:15], v[20:21], v[22:23] neg_lo:[0,0,1]
	v_add_u32_e32 v31, v31, v24
	v_pk_add_f32 v[20:21], v[22:23], v[50:51]
	global_load_dword v50, v[18:19], off
	v_lshl_add_u64 v[18:19], v[18:19], 0, v[24:25]
	s_waitcnt vmcnt(37)
	v_cndmask_b32_e64 v28, v20, v21, s[40:41]
	v_mov_b32_e32 v53, v52
	v_cvt_f16_f32_e32 v28, v28
	v_pk_mul_f32 v[22:23], v[16:17], v[20:21] op_sel:[0,1] op_sel_hi:[1,0]
	v_permlane32_swap_b32_e32 v52, v53
	global_store_short v31, v28, s[6:7]
	v_pk_fma_f32 v[22:23], v[14:15], v[20:21], v[22:23] neg_lo:[0,0,1]
	v_add_u32_e32 v31, v31, v24
	v_pk_add_f32 v[20:21], v[22:23], v[52:53]
	global_load_dword v52, v[18:19], off
	v_lshl_add_u64 v[18:19], v[18:19], 0, v[24:25]
	s_waitcnt vmcnt(38)
	v_cndmask_b32_e64 v28, v20, v21, s[40:41]
	v_mov_b32_e32 v55, v54
	v_cvt_f16_f32_e32 v28, v28
	v_pk_mul_f32 v[22:23], v[16:17], v[20:21] op_sel:[0,1] op_sel_hi:[1,0]
	v_permlane32_swap_b32_e32 v54, v55
	global_store_short v31, v28, s[6:7]
	v_pk_fma_f32 v[22:23], v[14:15], v[20:21], v[22:23] neg_lo:[0,0,1]
	v_add_u32_e32 v31, v31, v24
	v_pk_add_f32 v[20:21], v[22:23], v[54:55]
	global_load_dword v54, v[18:19], off
	v_lshl_add_u64 v[18:19], v[18:19], 0, v[24:25]
	s_waitcnt vmcnt(39)
	v_cndmask_b32_e64 v28, v20, v21, s[40:41]
	v_mov_b32_e32 v57, v56
	v_cvt_f16_f32_e32 v28, v28
	v_pk_mul_f32 v[22:23], v[16:17], v[20:21] op_sel:[0,1] op_sel_hi:[1,0]
	v_permlane32_swap_b32_e32 v56, v57
	global_store_short v31, v28, s[6:7]
	v_pk_fma_f32 v[22:23], v[14:15], v[20:21], v[22:23] neg_lo:[0,0,1]
	v_add_u32_e32 v31, v31, v24
	v_pk_add_f32 v[20:21], v[22:23], v[56:57]
	global_load_dword v56, v[18:19], off
	v_lshl_add_u64 v[18:19], v[18:19], 0, v[24:25]
	s_waitcnt vmcnt(40)
	v_cndmask_b32_e64 v28, v20, v21, s[40:41]
	v_mov_b32_e32 v59, v58
	v_cvt_f16_f32_e32 v28, v28
	v_pk_mul_f32 v[22:23], v[16:17], v[20:21] op_sel:[0,1] op_sel_hi:[1,0]
	v_permlane32_swap_b32_e32 v58, v59
	global_store_short v31, v28, s[6:7]
	v_pk_fma_f32 v[22:23], v[14:15], v[20:21], v[22:23] neg_lo:[0,0,1]
	v_add_u32_e32 v31, v31, v24
	v_pk_add_f32 v[20:21], v[22:23], v[58:59]
	global_load_dword v58, v[18:19], off
	v_lshl_add_u64 v[18:19], v[18:19], 0, v[24:25]
	s_waitcnt vmcnt(41)
	v_cndmask_b32_e64 v28, v20, v21, s[40:41]
	v_mov_b32_e32 v61, v60
	v_cvt_f16_f32_e32 v28, v28
	v_pk_mul_f32 v[22:23], v[16:17], v[20:21] op_sel:[0,1] op_sel_hi:[1,0]
	v_permlane32_swap_b32_e32 v60, v61
	global_store_short v31, v28, s[6:7]
	v_pk_fma_f32 v[22:23], v[14:15], v[20:21], v[22:23] neg_lo:[0,0,1]
	v_add_u32_e32 v31, v31, v24
	v_pk_add_f32 v[20:21], v[22:23], v[60:61]
	global_load_dword v60, v[18:19], off
	v_lshl_add_u64 v[18:19], v[18:19], 0, v[24:25]
	s_waitcnt vmcnt(42)
	v_cndmask_b32_e64 v28, v20, v21, s[40:41]
	v_mov_b32_e32 v63, v62
	v_cvt_f16_f32_e32 v28, v28
	v_pk_mul_f32 v[22:23], v[16:17], v[20:21] op_sel:[0,1] op_sel_hi:[1,0]
	v_permlane32_swap_b32_e32 v62, v63
	global_store_short v31, v28, s[6:7]
	v_pk_fma_f32 v[22:23], v[14:15], v[20:21], v[22:23] neg_lo:[0,0,1]
	v_add_u32_e32 v31, v31, v24
	v_pk_add_f32 v[20:21], v[22:23], v[62:63]
	global_load_dword v62, v[18:19], off
	v_lshl_add_u64 v[18:19], v[18:19], 0, v[24:25]
	s_waitcnt vmcnt(43)
	v_cndmask_b32_e64 v28, v20, v21, s[40:41]
	v_mov_b32_e32 v65, v64
	v_cvt_f16_f32_e32 v28, v28
	v_pk_mul_f32 v[22:23], v[16:17], v[20:21] op_sel:[0,1] op_sel_hi:[1,0]
	v_permlane32_swap_b32_e32 v64, v65
	global_store_short v31, v28, s[6:7]
	v_pk_fma_f32 v[22:23], v[14:15], v[20:21], v[22:23] neg_lo:[0,0,1]
	v_add_u32_e32 v31, v31, v24
	v_pk_add_f32 v[20:21], v[22:23], v[64:65]
	global_load_dword v64, v[18:19], off
	v_lshl_add_u64 v[18:19], v[18:19], 0, v[24:25]
	s_waitcnt vmcnt(44)
	v_cndmask_b32_e64 v28, v20, v21, s[40:41]
	v_mov_b32_e32 v67, v66
	v_cvt_f16_f32_e32 v28, v28
	v_pk_mul_f32 v[22:23], v[16:17], v[20:21] op_sel:[0,1] op_sel_hi:[1,0]
	v_permlane32_swap_b32_e32 v66, v67
	global_store_short v31, v28, s[6:7]
	v_pk_fma_f32 v[22:23], v[14:15], v[20:21], v[22:23] neg_lo:[0,0,1]
	v_add_u32_e32 v31, v31, v24
	v_pk_add_f32 v[20:21], v[22:23], v[66:67]
	global_load_dword v66, v[18:19], off
	v_lshl_add_u64 v[18:19], v[18:19], 0, v[24:25]
	s_waitcnt vmcnt(45)
	v_cndmask_b32_e64 v28, v20, v21, s[40:41]
	v_mov_b32_e32 v69, v68
	v_cvt_f16_f32_e32 v28, v28
	v_pk_mul_f32 v[22:23], v[16:17], v[20:21] op_sel:[0,1] op_sel_hi:[1,0]
	v_permlane32_swap_b32_e32 v68, v69
	global_store_short v31, v28, s[6:7]
	v_pk_fma_f32 v[22:23], v[14:15], v[20:21], v[22:23] neg_lo:[0,0,1]
	v_add_u32_e32 v31, v31, v24
	v_pk_add_f32 v[20:21], v[22:23], v[68:69]
	global_load_dword v68, v[18:19], off
	v_lshl_add_u64 v[18:19], v[18:19], 0, v[24:25]
	s_waitcnt vmcnt(46)
	v_cndmask_b32_e64 v28, v20, v21, s[40:41]
	v_mov_b32_e32 v71, v70
	v_cvt_f16_f32_e32 v28, v28
	v_pk_mul_f32 v[22:23], v[16:17], v[20:21] op_sel:[0,1] op_sel_hi:[1,0]
	v_permlane32_swap_b32_e32 v70, v71
	global_store_short v31, v28, s[6:7]
	v_pk_fma_f32 v[22:23], v[14:15], v[20:21], v[22:23] neg_lo:[0,0,1]
	v_add_u32_e32 v31, v31, v24
	v_pk_add_f32 v[20:21], v[22:23], v[70:71]
	global_load_dword v70, v[18:19], off
	v_lshl_add_u64 v[18:19], v[18:19], 0, v[24:25]
	v_mov_b32_e32 v31, v30
	s_waitcnt vmcnt(47)
	v_cndmask_b32_e64 v28, v20, v21, s[40:41]
	v_mov_b32_e32 v73, v72
	v_cvt_f16_f32_e32 v28, v28
	v_pk_mul_f32 v[22:23], v[16:17], v[20:21] op_sel:[0,1] op_sel_hi:[1,0]
	v_permlane32_swap_b32_e32 v72, v73
	global_store_short v31, v28, s[6:7]
	v_pk_fma_f32 v[22:23], v[14:15], v[20:21], v[22:23] neg_lo:[0,0,1]
	v_add_u32_e32 v31, v31, v24
	v_pk_add_f32 v[20:21], v[22:23], v[72:73]
	global_load_dword v72, v[18:19], off
	v_lshl_add_u64 v[18:19], v[18:19], 0, v[24:25]
	s_waitcnt vmcnt(48)
	v_cndmask_b32_e64 v28, v20, v21, s[40:41]
	v_mov_b32_e32 v75, v74
	v_cvt_f16_f32_e32 v28, v28
	v_pk_mul_f32 v[22:23], v[16:17], v[20:21] op_sel:[0,1] op_sel_hi:[1,0]
	v_permlane32_swap_b32_e32 v74, v75
	global_store_short v31, v28, s[6:7]
	v_pk_fma_f32 v[22:23], v[14:15], v[20:21], v[22:23] neg_lo:[0,0,1]
	v_add_u32_e32 v31, v31, v24
	v_pk_add_f32 v[20:21], v[22:23], v[74:75]
	global_load_dword v74, v[18:19], off
	v_lshl_add_u64 v[18:19], v[18:19], 0, v[24:25]
	s_waitcnt vmcnt(49)
	v_cndmask_b32_e64 v28, v20, v21, s[40:41]
	v_mov_b32_e32 v77, v76
	v_cvt_f16_f32_e32 v28, v28
	v_pk_mul_f32 v[22:23], v[16:17], v[20:21] op_sel:[0,1] op_sel_hi:[1,0]
	v_permlane32_swap_b32_e32 v76, v77
	global_store_short v31, v28, s[6:7]
	v_pk_fma_f32 v[22:23], v[14:15], v[20:21], v[22:23] neg_lo:[0,0,1]
	v_add_u32_e32 v31, v31, v24
	v_pk_add_f32 v[20:21], v[22:23], v[76:77]
	global_load_dword v76, v[18:19], off
	v_lshl_add_u64 v[18:19], v[18:19], 0, v[24:25]
	s_waitcnt vmcnt(50)
	v_cndmask_b32_e64 v28, v20, v21, s[40:41]
	v_mov_b32_e32 v79, v78
	v_cvt_f16_f32_e32 v28, v28
	v_pk_mul_f32 v[22:23], v[16:17], v[20:21] op_sel:[0,1] op_sel_hi:[1,0]
	v_permlane32_swap_b32_e32 v78, v79
	global_store_short v31, v28, s[6:7]
	v_pk_fma_f32 v[22:23], v[14:15], v[20:21], v[22:23] neg_lo:[0,0,1]
	v_add_u32_e32 v31, v31, v24
	v_pk_add_f32 v[20:21], v[22:23], v[78:79]
	global_load_dword v78, v[18:19], off
	v_lshl_add_u64 v[18:19], v[18:19], 0, v[24:25]
	s_waitcnt vmcnt(51)
	v_cndmask_b32_e64 v28, v20, v21, s[40:41]
	v_mov_b32_e32 v81, v80
	v_cvt_f16_f32_e32 v28, v28
	v_pk_mul_f32 v[22:23], v[16:17], v[20:21] op_sel:[0,1] op_sel_hi:[1,0]
	v_permlane32_swap_b32_e32 v80, v81
	global_store_short v31, v28, s[6:7]
	v_pk_fma_f32 v[22:23], v[14:15], v[20:21], v[22:23] neg_lo:[0,0,1]
	v_add_u32_e32 v31, v31, v24
	v_pk_add_f32 v[20:21], v[22:23], v[80:81]
	global_load_dword v80, v[18:19], off
	v_lshl_add_u64 v[18:19], v[18:19], 0, v[24:25]
	s_waitcnt vmcnt(52)
	v_cndmask_b32_e64 v28, v20, v21, s[40:41]
	v_mov_b32_e32 v83, v82
	v_cvt_f16_f32_e32 v28, v28
	v_pk_mul_f32 v[22:23], v[16:17], v[20:21] op_sel:[0,1] op_sel_hi:[1,0]
	v_permlane32_swap_b32_e32 v82, v83
	global_store_short v31, v28, s[6:7]
	v_pk_fma_f32 v[22:23], v[14:15], v[20:21], v[22:23] neg_lo:[0,0,1]
	v_add_u32_e32 v31, v31, v24
	v_pk_add_f32 v[20:21], v[22:23], v[82:83]
	global_load_dword v82, v[18:19], off
	v_lshl_add_u64 v[18:19], v[18:19], 0, v[24:25]
	s_waitcnt vmcnt(53)
	v_cndmask_b32_e64 v28, v20, v21, s[40:41]
	v_mov_b32_e32 v85, v84
	v_cvt_f16_f32_e32 v28, v28
	v_pk_mul_f32 v[22:23], v[16:17], v[20:21] op_sel:[0,1] op_sel_hi:[1,0]
	v_permlane32_swap_b32_e32 v84, v85
	global_store_short v31, v28, s[6:7]
	v_pk_fma_f32 v[22:23], v[14:15], v[20:21], v[22:23] neg_lo:[0,0,1]
	v_add_u32_e32 v31, v31, v24
	v_pk_add_f32 v[20:21], v[22:23], v[84:85]
	global_load_dword v84, v[18:19], off
	v_lshl_add_u64 v[18:19], v[18:19], 0, v[24:25]
	s_waitcnt vmcnt(54)
	v_cndmask_b32_e64 v28, v20, v21, s[40:41]
	v_mov_b32_e32 v87, v86
	v_cvt_f16_f32_e32 v28, v28
	v_pk_mul_f32 v[22:23], v[16:17], v[20:21] op_sel:[0,1] op_sel_hi:[1,0]
	v_permlane32_swap_b32_e32 v86, v87
	global_store_short v31, v28, s[6:7]
	v_pk_fma_f32 v[22:23], v[14:15], v[20:21], v[22:23] neg_lo:[0,0,1]
	v_add_u32_e32 v31, v31, v24
	v_pk_add_f32 v[20:21], v[22:23], v[86:87]
	global_load_dword v86, v[18:19], off
	v_lshl_add_u64 v[18:19], v[18:19], 0, v[24:25]
	s_waitcnt vmcnt(55)
	v_cndmask_b32_e64 v28, v20, v21, s[40:41]
	v_mov_b32_e32 v89, v88
	v_cvt_f16_f32_e32 v28, v28
	v_pk_mul_f32 v[22:23], v[16:17], v[20:21] op_sel:[0,1] op_sel_hi:[1,0]
	v_permlane32_swap_b32_e32 v88, v89
	global_store_short v31, v28, s[6:7]
	v_pk_fma_f32 v[22:23], v[14:15], v[20:21], v[22:23] neg_lo:[0,0,1]
	v_add_u32_e32 v31, v31, v24
	v_pk_add_f32 v[20:21], v[22:23], v[88:89]
	global_load_dword v88, v[18:19], off
	v_lshl_add_u64 v[18:19], v[18:19], 0, v[24:25]
	s_waitcnt vmcnt(56)
	v_cndmask_b32_e64 v28, v20, v21, s[40:41]
	v_mov_b32_e32 v91, v90
	v_cvt_f16_f32_e32 v28, v28
	v_pk_mul_f32 v[22:23], v[16:17], v[20:21] op_sel:[0,1] op_sel_hi:[1,0]
	v_permlane32_swap_b32_e32 v90, v91
	global_store_short v31, v28, s[6:7]
	v_pk_fma_f32 v[22:23], v[14:15], v[20:21], v[22:23] neg_lo:[0,0,1]
	v_add_u32_e32 v31, v31, v24
	v_pk_add_f32 v[20:21], v[22:23], v[90:91]
	global_load_dword v90, v[18:19], off
	v_lshl_add_u64 v[18:19], v[18:19], 0, v[24:25]
	s_waitcnt vmcnt(57)
	v_cndmask_b32_e64 v28, v20, v21, s[40:41]
	v_mov_b32_e32 v93, v92
	v_cvt_f16_f32_e32 v28, v28
	v_pk_mul_f32 v[22:23], v[16:17], v[20:21] op_sel:[0,1] op_sel_hi:[1,0]
	v_permlane32_swap_b32_e32 v92, v93
	global_store_short v31, v28, s[6:7]
	v_pk_fma_f32 v[22:23], v[14:15], v[20:21], v[22:23] neg_lo:[0,0,1]
	v_add_u32_e32 v31, v31, v24
	v_pk_add_f32 v[20:21], v[22:23], v[92:93]
	global_load_dword v92, v[18:19], off
	v_lshl_add_u64 v[18:19], v[18:19], 0, v[24:25]
	s_waitcnt vmcnt(58)
	v_cndmask_b32_e64 v28, v20, v21, s[40:41]
	v_mov_b32_e32 v95, v94
	v_cvt_f16_f32_e32 v28, v28
	v_pk_mul_f32 v[22:23], v[16:17], v[20:21] op_sel:[0,1] op_sel_hi:[1,0]
	v_permlane32_swap_b32_e32 v94, v95
	global_store_short v31, v28, s[6:7]
	v_pk_fma_f32 v[22:23], v[14:15], v[20:21], v[22:23] neg_lo:[0,0,1]
	v_add_u32_e32 v31, v31, v24
	v_pk_add_f32 v[20:21], v[22:23], v[94:95]
	global_load_dword v94, v[18:19], off
	v_lshl_add_u64 v[18:19], v[18:19], 0, v[24:25]
	s_waitcnt vmcnt(59)
	v_cndmask_b32_e64 v28, v20, v21, s[40:41]
	v_mov_b32_e32 v97, v96
	v_cvt_f16_f32_e32 v28, v28
	v_pk_mul_f32 v[22:23], v[16:17], v[20:21] op_sel:[0,1] op_sel_hi:[1,0]
	v_permlane32_swap_b32_e32 v96, v97
	global_store_short v31, v28, s[6:7]
	v_pk_fma_f32 v[22:23], v[14:15], v[20:21], v[22:23] neg_lo:[0,0,1]
	v_add_u32_e32 v31, v31, v24
	v_pk_add_f32 v[20:21], v[22:23], v[96:97]
	global_load_dword v96, v[18:19], off
	v_lshl_add_u64 v[18:19], v[18:19], 0, v[24:25]
	s_waitcnt vmcnt(60)
	v_cndmask_b32_e64 v28, v20, v21, s[40:41]
	v_mov_b32_e32 v99, v98
	v_cvt_f16_f32_e32 v28, v28
	v_pk_mul_f32 v[22:23], v[16:17], v[20:21] op_sel:[0,1] op_sel_hi:[1,0]
	v_permlane32_swap_b32_e32 v98, v99
	global_store_short v31, v28, s[6:7]
	v_pk_fma_f32 v[22:23], v[14:15], v[20:21], v[22:23] neg_lo:[0,0,1]
	v_add_u32_e32 v31, v31, v24
	v_pk_add_f32 v[20:21], v[22:23], v[98:99]
	global_load_dword v98, v[18:19], off
	v_lshl_add_u64 v[18:19], v[18:19], 0, v[24:25]
	s_waitcnt vmcnt(61)
	v_cndmask_b32_e64 v28, v20, v21, s[40:41]
	v_mov_b32_e32 v101, v100
	v_cvt_f16_f32_e32 v28, v28
	v_pk_mul_f32 v[22:23], v[16:17], v[20:21] op_sel:[0,1] op_sel_hi:[1,0]
	v_permlane32_swap_b32_e32 v100, v101
	global_store_short v31, v28, s[6:7]
	v_pk_fma_f32 v[22:23], v[14:15], v[20:21], v[22:23] neg_lo:[0,0,1]
	v_add_u32_e32 v31, v31, v24
	v_pk_add_f32 v[20:21], v[22:23], v[100:101]
	global_load_dword v100, v[18:19], off
	v_lshl_add_u64 v[18:19], v[18:19], 0, v[24:25]
	s_waitcnt vmcnt(62)
	v_cndmask_b32_e64 v28, v20, v21, s[40:41]
	v_mov_b32_e32 v103, v102
	v_cvt_f16_f32_e32 v28, v28
	v_pk_mul_f32 v[22:23], v[16:17], v[20:21] op_sel:[0,1] op_sel_hi:[1,0]
	v_permlane32_swap_b32_e32 v102, v103
	global_store_short v31, v28, s[6:7]
	v_pk_fma_f32 v[22:23], v[14:15], v[20:21], v[22:23] neg_lo:[0,0,1]
	v_add_u32_e32 v31, v31, v24
	v_pk_add_f32 v[20:21], v[22:23], v[102:103]
	global_load_dword v102, v[18:19], off
	v_lshl_add_u64 v[18:19], v[18:19], 0, v[24:25]
	s_movk_i32 s34, 15
.Ls5scan_loop:
	s_waitcnt vmcnt(62)
	v_cndmask_b32_e64 v28, v20, v21, s[40:41]
	v_mov_b32_e32 v41, v40
	v_cvt_f16_f32_e32 v28, v28
	v_pk_mul_f32 v[22:23], v[16:17], v[20:21] op_sel:[0,1] op_sel_hi:[1,0]
	v_permlane32_swap_b32_e32 v40, v41
	global_store_short v31, v28, s[6:7]
	v_pk_fma_f32 v[22:23], v[14:15], v[20:21], v[22:23] neg_lo:[0,0,1]
	v_add_u32_e32 v31, v31, v24
	v_pk_add_f32 v[20:21], v[22:23], v[40:41]
	global_load_dword v40, v[18:19], off
	v_lshl_add_u64 v[18:19], v[18:19], 0, v[24:25]
	s_waitcnt vmcnt(62)
	v_cndmask_b32_e64 v28, v20, v21, s[40:41]
	v_mov_b32_e32 v43, v42
	v_cvt_f16_f32_e32 v28, v28
	v_pk_mul_f32 v[22:23], v[16:17], v[20:21] op_sel:[0,1] op_sel_hi:[1,0]
	v_permlane32_swap_b32_e32 v42, v43
	global_store_short v31, v28, s[6:7]
	v_pk_fma_f32 v[22:23], v[14:15], v[20:21], v[22:23] neg_lo:[0,0,1]
	v_add_u32_e32 v31, v31, v24
	v_pk_add_f32 v[20:21], v[22:23], v[42:43]
	global_load_dword v42, v[18:19], off
	v_lshl_add_u64 v[18:19], v[18:19], 0, v[24:25]
	s_waitcnt vmcnt(62)
	v_cndmask_b32_e64 v28, v20, v21, s[40:41]
	v_mov_b32_e32 v45, v44
	v_cvt_f16_f32_e32 v28, v28
	v_pk_mul_f32 v[22:23], v[16:17], v[20:21] op_sel:[0,1] op_sel_hi:[1,0]
	v_permlane32_swap_b32_e32 v44, v45
	global_store_short v31, v28, s[6:7]
	v_pk_fma_f32 v[22:23], v[14:15], v[20:21], v[22:23] neg_lo:[0,0,1]
	v_add_u32_e32 v31, v31, v24
	v_pk_add_f32 v[20:21], v[22:23], v[44:45]
	global_load_dword v44, v[18:19], off
	v_lshl_add_u64 v[18:19], v[18:19], 0, v[24:25]
	s_waitcnt vmcnt(62)
	v_cndmask_b32_e64 v28, v20, v21, s[40:41]
	v_mov_b32_e32 v47, v46
	v_cvt_f16_f32_e32 v28, v28
	v_pk_mul_f32 v[22:23], v[16:17], v[20:21] op_sel:[0,1] op_sel_hi:[1,0]
	v_permlane32_swap_b32_e32 v46, v47
	global_store_short v31, v28, s[6:7]
	v_pk_fma_f32 v[22:23], v[14:15], v[20:21], v[22:23] neg_lo:[0,0,1]
	v_add_u32_e32 v31, v31, v24
	v_pk_add_f32 v[20:21], v[22:23], v[46:47]
	global_load_dword v46, v[18:19], off
	v_lshl_add_u64 v[18:19], v[18:19], 0, v[24:25]
	s_waitcnt vmcnt(62)
	v_cndmask_b32_e64 v28, v20, v21, s[40:41]
	v_mov_b32_e32 v49, v48
	v_cvt_f16_f32_e32 v28, v28
	v_pk_mul_f32 v[22:23], v[16:17], v[20:21] op_sel:[0,1] op_sel_hi:[1,0]
	v_permlane32_swap_b32_e32 v48, v49
	global_store_short v31, v28, s[6:7]
	v_pk_fma_f32 v[22:23], v[14:15], v[20:21], v[22:23] neg_lo:[0,0,1]
	v_add_u32_e32 v31, v31, v24
	v_pk_add_f32 v[20:21], v[22:23], v[48:49]
	global_load_dword v48, v[18:19], off
	v_lshl_add_u64 v[18:19], v[18:19], 0, v[24:25]
	s_waitcnt vmcnt(62)
	v_cndmask_b32_e64 v28, v20, v21, s[40:41]
	v_mov_b32_e32 v51, v50
	v_cvt_f16_f32_e32 v28, v28
	v_pk_mul_f32 v[22:23], v[16:17], v[20:21] op_sel:[0,1] op_sel_hi:[1,0]
	v_permlane32_swap_b32_e32 v50, v51
	global_store_short v31, v28, s[6:7]
	v_pk_fma_f32 v[22:23], v[14:15], v[20:21], v[22:23] neg_lo:[0,0,1]
	v_add_u32_e32 v31, v31, v24
	v_pk_add_f32 v[20:21], v[22:23], v[50:51]
	global_load_dword v50, v[18:19], off
	v_lshl_add_u64 v[18:19], v[18:19], 0, v[24:25]
	s_waitcnt vmcnt(62)
	v_cndmask_b32_e64 v28, v20, v21, s[40:41]
	v_mov_b32_e32 v53, v52
	v_cvt_f16_f32_e32 v28, v28
	v_pk_mul_f32 v[22:23], v[16:17], v[20:21] op_sel:[0,1] op_sel_hi:[1,0]
	v_permlane32_swap_b32_e32 v52, v53
	global_store_short v31, v28, s[6:7]
	v_pk_fma_f32 v[22:23], v[14:15], v[20:21], v[22:23] neg_lo:[0,0,1]
	v_add_u32_e32 v31, v31, v24
	v_pk_add_f32 v[20:21], v[22:23], v[52:53]
	global_load_dword v52, v[18:19], off
	v_lshl_add_u64 v[18:19], v[18:19], 0, v[24:25]
	s_waitcnt vmcnt(62)
	v_cndmask_b32_e64 v28, v20, v21, s[40:41]
	v_mov_b32_e32 v55, v54
	v_cvt_f16_f32_e32 v28, v28
	v_pk_mul_f32 v[22:23], v[16:17], v[20:21] op_sel:[0,1] op_sel_hi:[1,0]
	v_permlane32_swap_b32_e32 v54, v55
	global_store_short v31, v28, s[6:7]
	v_pk_fma_f32 v[22:23], v[14:15], v[20:21], v[22:23] neg_lo:[0,0,1]
	v_add_u32_e32 v31, v31, v24
	v_pk_add_f32 v[20:21], v[22:23], v[54:55]
	global_load_dword v54, v[18:19], off
	v_lshl_add_u64 v[18:19], v[18:19], 0, v[24:25]
	s_waitcnt vmcnt(62)
	v_cndmask_b32_e64 v28, v20, v21, s[40:41]
	v_mov_b32_e32 v57, v56
	v_cvt_f16_f32_e32 v28, v28
	v_pk_mul_f32 v[22:23], v[16:17], v[20:21] op_sel:[0,1] op_sel_hi:[1,0]
	v_permlane32_swap_b32_e32 v56, v57
	global_store_short v31, v28, s[6:7]
	v_pk_fma_f32 v[22:23], v[14:15], v[20:21], v[22:23] neg_lo:[0,0,1]
	v_add_u32_e32 v31, v31, v24
	v_pk_add_f32 v[20:21], v[22:23], v[56:57]
	global_load_dword v56, v[18:19], off
	v_lshl_add_u64 v[18:19], v[18:19], 0, v[24:25]
	s_waitcnt vmcnt(62)
	v_cndmask_b32_e64 v28, v20, v21, s[40:41]
	v_mov_b32_e32 v59, v58
	v_cvt_f16_f32_e32 v28, v28
	v_pk_mul_f32 v[22:23], v[16:17], v[20:21] op_sel:[0,1] op_sel_hi:[1,0]
	v_permlane32_swap_b32_e32 v58, v59
	global_store_short v31, v28, s[6:7]
	v_pk_fma_f32 v[22:23], v[14:15], v[20:21], v[22:23] neg_lo:[0,0,1]
	v_add_u32_e32 v31, v31, v24
	v_pk_add_f32 v[20:21], v[22:23], v[58:59]
	global_load_dword v58, v[18:19], off
	v_lshl_add_u64 v[18:19], v[18:19], 0, v[24:25]
	s_waitcnt vmcnt(62)
	v_cndmask_b32_e64 v28, v20, v21, s[40:41]
	v_mov_b32_e32 v61, v60
	v_cvt_f16_f32_e32 v28, v28
	v_pk_mul_f32 v[22:23], v[16:17], v[20:21] op_sel:[0,1] op_sel_hi:[1,0]
	v_permlane32_swap_b32_e32 v60, v61
	global_store_short v31, v28, s[6:7]
	v_pk_fma_f32 v[22:23], v[14:15], v[20:21], v[22:23] neg_lo:[0,0,1]
	v_add_u32_e32 v31, v31, v24
	v_pk_add_f32 v[20:21], v[22:23], v[60:61]
	global_load_dword v60, v[18:19], off
	v_lshl_add_u64 v[18:19], v[18:19], 0, v[24:25]
	s_waitcnt vmcnt(62)
	v_cndmask_b32_e64 v28, v20, v21, s[40:41]
	v_mov_b32_e32 v63, v62
	v_cvt_f16_f32_e32 v28, v28
	v_pk_mul_f32 v[22:23], v[16:17], v[20:21] op_sel:[0,1] op_sel_hi:[1,0]
	v_permlane32_swap_b32_e32 v62, v63
	global_store_short v31, v28, s[6:7]
	v_pk_fma_f32 v[22:23], v[14:15], v[20:21], v[22:23] neg_lo:[0,0,1]
	v_add_u32_e32 v31, v31, v24
	v_pk_add_f32 v[20:21], v[22:23], v[62:63]
	global_load_dword v62, v[18:19], off
	v_lshl_add_u64 v[18:19], v[18:19], 0, v[24:25]
	s_waitcnt vmcnt(62)
	v_cndmask_b32_e64 v28, v20, v21, s[40:41]
	v_mov_b32_e32 v65, v64
	v_cvt_f16_f32_e32 v28, v28
	v_pk_mul_f32 v[22:23], v[16:17], v[20:21] op_sel:[0,1] op_sel_hi:[1,0]
	v_permlane32_swap_b32_e32 v64, v65
	global_store_short v31, v28, s[6:7]
	v_pk_fma_f32 v[22:23], v[14:15], v[20:21], v[22:23] neg_lo:[0,0,1]
	v_add_u32_e32 v31, v31, v24
	v_pk_add_f32 v[20:21], v[22:23], v[64:65]
	global_load_dword v64, v[18:19], off
	v_lshl_add_u64 v[18:19], v[18:19], 0, v[24:25]
	s_waitcnt vmcnt(62)
	v_cndmask_b32_e64 v28, v20, v21, s[40:41]
	v_mov_b32_e32 v67, v66
	v_cvt_f16_f32_e32 v28, v28
	v_pk_mul_f32 v[22:23], v[16:17], v[20:21] op_sel:[0,1] op_sel_hi:[1,0]
	v_permlane32_swap_b32_e32 v66, v67
	global_store_short v31, v28, s[6:7]
	v_pk_fma_f32 v[22:23], v[14:15], v[20:21], v[22:23] neg_lo:[0,0,1]
	v_add_u32_e32 v31, v31, v24
	v_pk_add_f32 v[20:21], v[22:23], v[66:67]
	global_load_dword v66, v[18:19], off
	v_lshl_add_u64 v[18:19], v[18:19], 0, v[24:25]
	s_waitcnt vmcnt(62)
	v_cndmask_b32_e64 v28, v20, v21, s[40:41]
	v_mov_b32_e32 v69, v68
	v_cvt_f16_f32_e32 v28, v28
	v_pk_mul_f32 v[22:23], v[16:17], v[20:21] op_sel:[0,1] op_sel_hi:[1,0]
	v_permlane32_swap_b32_e32 v68, v69
	global_store_short v31, v28, s[6:7]
	v_pk_fma_f32 v[22:23], v[14:15], v[20:21], v[22:23] neg_lo:[0,0,1]
	v_add_u32_e32 v31, v31, v24
	v_pk_add_f32 v[20:21], v[22:23], v[68:69]
	global_load_dword v68, v[18:19], off
	v_lshl_add_u64 v[18:19], v[18:19], 0, v[24:25]
	s_waitcnt vmcnt(62)
	v_cndmask_b32_e64 v28, v20, v21, s[40:41]
	v_mov_b32_e32 v71, v70
	v_cvt_f16_f32_e32 v28, v28
	v_pk_mul_f32 v[22:23], v[16:17], v[20:21] op_sel:[0,1] op_sel_hi:[1,0]
	v_permlane32_swap_b32_e32 v70, v71
	global_store_short v31, v28, s[6:7]
	v_pk_fma_f32 v[22:23], v[14:15], v[20:21], v[22:23] neg_lo:[0,0,1]
	v_add_u32_e32 v31, v31, v24
	v_pk_add_f32 v[20:21], v[22:23], v[70:71]
	global_load_dword v70, v[18:19], off
	v_lshl_add_u64 v[18:19], v[18:19], 0, v[24:25]
	s_waitcnt vmcnt(62)
	v_cndmask_b32_e64 v28, v20, v21, s[40:41]
	v_mov_b32_e32 v73, v72
	v_cvt_f16_f32_e32 v28, v28
	v_pk_mul_f32 v[22:23], v[16:17], v[20:21] op_sel:[0,1] op_sel_hi:[1,0]
	v_permlane32_swap_b32_e32 v72, v73
	global_store_short v31, v28, s[6:7]
	v_pk_fma_f32 v[22:23], v[14:15], v[20:21], v[22:23] neg_lo:[0,0,1]
	v_add_u32_e32 v31, v31, v24
	v_pk_add_f32 v[20:21], v[22:23], v[72:73]
	global_load_dword v72, v[18:19], off
	v_lshl_add_u64 v[18:19], v[18:19], 0, v[24:25]
	s_waitcnt vmcnt(62)
	v_cndmask_b32_e64 v28, v20, v21, s[40:41]
	v_mov_b32_e32 v75, v74
	v_cvt_f16_f32_e32 v28, v28
	v_pk_mul_f32 v[22:23], v[16:17], v[20:21] op_sel:[0,1] op_sel_hi:[1,0]
	v_permlane32_swap_b32_e32 v74, v75
	global_store_short v31, v28, s[6:7]
	v_pk_fma_f32 v[22:23], v[14:15], v[20:21], v[22:23] neg_lo:[0,0,1]
	v_add_u32_e32 v31, v31, v24
	v_pk_add_f32 v[20:21], v[22:23], v[74:75]
	global_load_dword v74, v[18:19], off
	v_lshl_add_u64 v[18:19], v[18:19], 0, v[24:25]
	s_waitcnt vmcnt(62)
	v_cndmask_b32_e64 v28, v20, v21, s[40:41]
	v_mov_b32_e32 v77, v76
	v_cvt_f16_f32_e32 v28, v28
	v_pk_mul_f32 v[22:23], v[16:17], v[20:21] op_sel:[0,1] op_sel_hi:[1,0]
	v_permlane32_swap_b32_e32 v76, v77
	global_store_short v31, v28, s[6:7]
	v_pk_fma_f32 v[22:23], v[14:15], v[20:21], v[22:23] neg_lo:[0,0,1]
	v_add_u32_e32 v31, v31, v24
	v_pk_add_f32 v[20:21], v[22:23], v[76:77]
	global_load_dword v76, v[18:19], off
	v_lshl_add_u64 v[18:19], v[18:19], 0, v[24:25]
	s_waitcnt vmcnt(62)
	v_cndmask_b32_e64 v28, v20, v21, s[40:41]
	v_mov_b32_e32 v79, v78
	v_cvt_f16_f32_e32 v28, v28
	v_pk_mul_f32 v[22:23], v[16:17], v[20:21] op_sel:[0,1] op_sel_hi:[1,0]
	v_permlane32_swap_b32_e32 v78, v79
	global_store_short v31, v28, s[6:7]
	v_pk_fma_f32 v[22:23], v[14:15], v[20:21], v[22:23] neg_lo:[0,0,1]
	v_add_u32_e32 v31, v31, v24
	v_pk_add_f32 v[20:21], v[22:23], v[78:79]
	global_load_dword v78, v[18:19], off
	v_lshl_add_u64 v[18:19], v[18:19], 0, v[24:25]
	s_waitcnt vmcnt(62)
	v_cndmask_b32_e64 v28, v20, v21, s[40:41]
	v_mov_b32_e32 v81, v80
	v_cvt_f16_f32_e32 v28, v28
	v_pk_mul_f32 v[22:23], v[16:17], v[20:21] op_sel:[0,1] op_sel_hi:[1,0]
	v_permlane32_swap_b32_e32 v80, v81
	global_store_short v31, v28, s[6:7]
	v_pk_fma_f32 v[22:23], v[14:15], v[20:21], v[22:23] neg_lo:[0,0,1]
	v_add_u32_e32 v31, v31, v24
	v_pk_add_f32 v[20:21], v[22:23], v[80:81]
	global_load_dword v80, v[18:19], off
	v_lshl_add_u64 v[18:19], v[18:19], 0, v[24:25]
	s_waitcnt vmcnt(62)
	v_cndmask_b32_e64 v28, v20, v21, s[40:41]
	v_mov_b32_e32 v83, v82
	v_cvt_f16_f32_e32 v28, v28
	v_pk_mul_f32 v[22:23], v[16:17], v[20:21] op_sel:[0,1] op_sel_hi:[1,0]
	v_permlane32_swap_b32_e32 v82, v83
	global_store_short v31, v28, s[6:7]
	v_pk_fma_f32 v[22:23], v[14:15], v[20:21], v[22:23] neg_lo:[0,0,1]
	v_add_u32_e32 v31, v31, v24
	v_pk_add_f32 v[20:21], v[22:23], v[82:83]
	global_load_dword v82, v[18:19], off
	v_lshl_add_u64 v[18:19], v[18:19], 0, v[24:25]
	s_waitcnt vmcnt(62)
	v_cndmask_b32_e64 v28, v20, v21, s[40:41]
	v_mov_b32_e32 v85, v84
	v_cvt_f16_f32_e32 v28, v28
	v_pk_mul_f32 v[22:23], v[16:17], v[20:21] op_sel:[0,1] op_sel_hi:[1,0]
	v_permlane32_swap_b32_e32 v84, v85
	global_store_short v31, v28, s[6:7]
	v_pk_fma_f32 v[22:23], v[14:15], v[20:21], v[22:23] neg_lo:[0,0,1]
	v_add_u32_e32 v31, v31, v24
	v_pk_add_f32 v[20:21], v[22:23], v[84:85]
	global_load_dword v84, v[18:19], off
	v_lshl_add_u64 v[18:19], v[18:19], 0, v[24:25]
	s_waitcnt vmcnt(62)
	v_cndmask_b32_e64 v28, v20, v21, s[40:41]
	v_mov_b32_e32 v87, v86
	v_cvt_f16_f32_e32 v28, v28
	v_pk_mul_f32 v[22:23], v[16:17], v[20:21] op_sel:[0,1] op_sel_hi:[1,0]
	v_permlane32_swap_b32_e32 v86, v87
	global_store_short v31, v28, s[6:7]
	v_pk_fma_f32 v[22:23], v[14:15], v[20:21], v[22:23] neg_lo:[0,0,1]
	v_add_u32_e32 v31, v31, v24
	v_pk_add_f32 v[20:21], v[22:23], v[86:87]
	global_load_dword v86, v[18:19], off
	v_lshl_add_u64 v[18:19], v[18:19], 0, v[24:25]
	s_waitcnt vmcnt(62)
	v_cndmask_b32_e64 v28, v20, v21, s[40:41]
	v_mov_b32_e32 v89, v88
	v_cvt_f16_f32_e32 v28, v28
	v_pk_mul_f32 v[22:23], v[16:17], v[20:21] op_sel:[0,1] op_sel_hi:[1,0]
	v_permlane32_swap_b32_e32 v88, v89
	global_store_short v31, v28, s[6:7]
	v_pk_fma_f32 v[22:23], v[14:15], v[20:21], v[22:23] neg_lo:[0,0,1]
	v_add_u32_e32 v31, v31, v24
	v_pk_add_f32 v[20:21], v[22:23], v[88:89]
	global_load_dword v88, v[18:19], off
	v_lshl_add_u64 v[18:19], v[18:19], 0, v[24:25]
	s_waitcnt vmcnt(62)
	v_cndmask_b32_e64 v28, v20, v21, s[40:41]
	v_mov_b32_e32 v91, v90
	v_cvt_f16_f32_e32 v28, v28
	v_pk_mul_f32 v[22:23], v[16:17], v[20:21] op_sel:[0,1] op_sel_hi:[1,0]
	v_permlane32_swap_b32_e32 v90, v91
	global_store_short v31, v28, s[6:7]
	v_pk_fma_f32 v[22:23], v[14:15], v[20:21], v[22:23] neg_lo:[0,0,1]
	v_add_u32_e32 v31, v31, v24
	v_pk_add_f32 v[20:21], v[22:23], v[90:91]
	global_load_dword v90, v[18:19], off
	v_lshl_add_u64 v[18:19], v[18:19], 0, v[24:25]
	s_waitcnt vmcnt(62)
	v_cndmask_b32_e64 v28, v20, v21, s[40:41]
	v_mov_b32_e32 v93, v92
	v_cvt_f16_f32_e32 v28, v28
	v_pk_mul_f32 v[22:23], v[16:17], v[20:21] op_sel:[0,1] op_sel_hi:[1,0]
	v_permlane32_swap_b32_e32 v92, v93
	global_store_short v31, v28, s[6:7]
	v_pk_fma_f32 v[22:23], v[14:15], v[20:21], v[22:23] neg_lo:[0,0,1]
	v_add_u32_e32 v31, v31, v24
	v_pk_add_f32 v[20:21], v[22:23], v[92:93]
	global_load_dword v92, v[18:19], off
	v_lshl_add_u64 v[18:19], v[18:19], 0, v[24:25]
	s_waitcnt vmcnt(62)
	v_cndmask_b32_e64 v28, v20, v21, s[40:41]
	v_mov_b32_e32 v95, v94
	v_cvt_f16_f32_e32 v28, v28
	v_pk_mul_f32 v[22:23], v[16:17], v[20:21] op_sel:[0,1] op_sel_hi:[1,0]
	v_permlane32_swap_b32_e32 v94, v95
	global_store_short v31, v28, s[6:7]
	v_pk_fma_f32 v[22:23], v[14:15], v[20:21], v[22:23] neg_lo:[0,0,1]
	v_add_u32_e32 v31, v31, v24
	v_pk_add_f32 v[20:21], v[22:23], v[94:95]
	global_load_dword v94, v[18:19], off
	v_lshl_add_u64 v[18:19], v[18:19], 0, v[24:25]
	s_waitcnt vmcnt(62)
	v_cndmask_b32_e64 v28, v20, v21, s[40:41]
	v_mov_b32_e32 v97, v96
	v_cvt_f16_f32_e32 v28, v28
	v_pk_mul_f32 v[22:23], v[16:17], v[20:21] op_sel:[0,1] op_sel_hi:[1,0]
	v_permlane32_swap_b32_e32 v96, v97
	global_store_short v31, v28, s[6:7]
	v_pk_fma_f32 v[22:23], v[14:15], v[20:21], v[22:23] neg_lo:[0,0,1]
	v_add_u32_e32 v31, v31, v24
	v_pk_add_f32 v[20:21], v[22:23], v[96:97]
	global_load_dword v96, v[18:19], off
	v_lshl_add_u64 v[18:19], v[18:19], 0, v[24:25]
	s_waitcnt vmcnt(62)
	v_cndmask_b32_e64 v28, v20, v21, s[40:41]
	v_mov_b32_e32 v99, v98
	v_cvt_f16_f32_e32 v28, v28
	v_pk_mul_f32 v[22:23], v[16:17], v[20:21] op_sel:[0,1] op_sel_hi:[1,0]
	v_permlane32_swap_b32_e32 v98, v99
	global_store_short v31, v28, s[6:7]
	v_pk_fma_f32 v[22:23], v[14:15], v[20:21], v[22:23] neg_lo:[0,0,1]
	v_add_u32_e32 v31, v31, v24
	v_pk_add_f32 v[20:21], v[22:23], v[98:99]
	global_load_dword v98, v[18:19], off
	v_lshl_add_u64 v[18:19], v[18:19], 0, v[24:25]
	s_waitcnt vmcnt(62)
	v_cndmask_b32_e64 v28, v20, v21, s[40:41]
	v_mov_b32_e32 v101, v100
	v_cvt_f16_f32_e32 v28, v28
	v_pk_mul_f32 v[22:23], v[16:17], v[20:21] op_sel:[0,1] op_sel_hi:[1,0]
	v_permlane32_swap_b32_e32 v100, v101
	global_store_short v31, v28, s[6:7]
	v_pk_fma_f32 v[22:23], v[14:15], v[20:21], v[22:23] neg_lo:[0,0,1]
	v_add_u32_e32 v31, v31, v24
	v_pk_add_f32 v[20:21], v[22:23], v[100:101]
	global_load_dword v100, v[18:19], off
	v_lshl_add_u64 v[18:19], v[18:19], 0, v[24:25]
	s_waitcnt vmcnt(62)
	v_cndmask_b32_e64 v28, v20, v21, s[40:41]
	v_mov_b32_e32 v103, v102
	v_cvt_f16_f32_e32 v28, v28
	v_pk_mul_f32 v[22:23], v[16:17], v[20:21] op_sel:[0,1] op_sel_hi:[1,0]
	v_permlane32_swap_b32_e32 v102, v103
	global_store_short v31, v28, s[6:7]
	v_pk_fma_f32 v[22:23], v[14:15], v[20:21], v[22:23] neg_lo:[0,0,1]
	v_add_u32_e32 v31, v31, v24
	v_pk_add_f32 v[20:21], v[22:23], v[102:103]
	global_load_dword v102, v[18:19], off
	v_lshl_add_u64 v[18:19], v[18:19], 0, v[24:25]
	s_sub_u32 s34, s34, 1
	s_cmp_lg_u32 s34, 0
	s_cbranch_scc1 .Ls5scan_loop
	s_waitcnt vmcnt(62)
	v_cndmask_b32_e64 v28, v20, v21, s[40:41]
	v_mov_b32_e32 v41, v40
	v_cvt_f16_f32_e32 v28, v28
	v_pk_mul_f32 v[22:23], v[16:17], v[20:21] op_sel:[0,1] op_sel_hi:[1,0]
	v_permlane32_swap_b32_e32 v40, v41
	global_store_short v31, v28, s[6:7]
	v_pk_fma_f32 v[22:23], v[14:15], v[20:21], v[22:23] neg_lo:[0,0,1]
	v_add_u32_e32 v31, v31, v24
	v_pk_add_f32 v[20:21], v[22:23], v[40:41]
	global_load_dword v40, v[18:19], off
	v_lshl_add_u64 v[18:19], v[18:19], 0, v[24:25]
	s_waitcnt vmcnt(62)
	v_cndmask_b32_e64 v28, v20, v21, s[40:41]
	v_mov_b32_e32 v43, v42
	v_cvt_f16_f32_e32 v28, v28
	v_pk_mul_f32 v[22:23], v[16:17], v[20:21] op_sel:[0,1] op_sel_hi:[1,0]
	v_permlane32_swap_b32_e32 v42, v43
	global_store_short v31, v28, s[6:7]
	v_pk_fma_f32 v[22:23], v[14:15], v[20:21], v[22:23] neg_lo:[0,0,1]
	v_add_u32_e32 v31, v31, v24
	v_pk_add_f32 v[20:21], v[22:23], v[42:43]
	global_load_dword v42, v[18:19], off
	v_lshl_add_u64 v[18:19], v[18:19], 0, v[24:25]
	s_waitcnt vmcnt(62)
	v_cndmask_b32_e64 v28, v20, v21, s[40:41]
	v_mov_b32_e32 v45, v44
	v_cvt_f16_f32_e32 v28, v28
	v_pk_mul_f32 v[22:23], v[16:17], v[20:21] op_sel:[0,1] op_sel_hi:[1,0]
	v_permlane32_swap_b32_e32 v44, v45
	global_store_short v31, v28, s[6:7]
	v_pk_fma_f32 v[22:23], v[14:15], v[20:21], v[22:23] neg_lo:[0,0,1]
	v_add_u32_e32 v31, v31, v24
	v_pk_add_f32 v[20:21], v[22:23], v[44:45]
	global_load_dword v44, v[18:19], off
	v_lshl_add_u64 v[18:19], v[18:19], 0, v[24:25]
	s_waitcnt vmcnt(62)
	v_cndmask_b32_e64 v28, v20, v21, s[40:41]
	v_mov_b32_e32 v47, v46
	v_cvt_f16_f32_e32 v28, v28
	v_pk_mul_f32 v[22:23], v[16:17], v[20:21] op_sel:[0,1] op_sel_hi:[1,0]
	v_permlane32_swap_b32_e32 v46, v47
	global_store_short v31, v28, s[6:7]
	v_pk_fma_f32 v[22:23], v[14:15], v[20:21], v[22:23] neg_lo:[0,0,1]
	v_add_u32_e32 v31, v31, v24
	v_pk_add_f32 v[20:21], v[22:23], v[46:47]
	global_load_dword v46, v[18:19], off
	v_lshl_add_u64 v[18:19], v[18:19], 0, v[24:25]
	s_waitcnt vmcnt(62)
	v_cndmask_b32_e64 v28, v20, v21, s[40:41]
	v_mov_b32_e32 v49, v48
	v_cvt_f16_f32_e32 v28, v28
	v_pk_mul_f32 v[22:23], v[16:17], v[20:21] op_sel:[0,1] op_sel_hi:[1,0]
	v_permlane32_swap_b32_e32 v48, v49
	global_store_short v31, v28, s[6:7]
	v_pk_fma_f32 v[22:23], v[14:15], v[20:21], v[22:23] neg_lo:[0,0,1]
	v_add_u32_e32 v31, v31, v24
	v_pk_add_f32 v[20:21], v[22:23], v[48:49]
	global_load_dword v48, v[18:19], off
	v_lshl_add_u64 v[18:19], v[18:19], 0, v[24:25]
	s_waitcnt vmcnt(62)
	v_cndmask_b32_e64 v28, v20, v21, s[40:41]
	v_mov_b32_e32 v51, v50
	v_cvt_f16_f32_e32 v28, v28
	v_pk_mul_f32 v[22:23], v[16:17], v[20:21] op_sel:[0,1] op_sel_hi:[1,0]
	v_permlane32_swap_b32_e32 v50, v51
	global_store_short v31, v28, s[6:7]
	v_pk_fma_f32 v[22:23], v[14:15], v[20:21], v[22:23] neg_lo:[0,0,1]
	v_add_u32_e32 v31, v31, v24
	v_pk_add_f32 v[20:21], v[22:23], v[50:51]
	global_load_dword v50, v[18:19], off
	v_lshl_add_u64 v[18:19], v[18:19], 0, v[24:25]
	s_waitcnt vmcnt(62)
	v_cndmask_b32_e64 v28, v20, v21, s[40:41]
	v_mov_b32_e32 v53, v52
	v_cvt_f16_f32_e32 v28, v28
	v_pk_mul_f32 v[22:23], v[16:17], v[20:21] op_sel:[0,1] op_sel_hi:[1,0]
	v_permlane32_swap_b32_e32 v52, v53
	global_store_short v31, v28, s[6:7]
	v_pk_fma_f32 v[22:23], v[14:15], v[20:21], v[22:23] neg_lo:[0,0,1]
	v_add_u32_e32 v31, v31, v24
	v_pk_add_f32 v[20:21], v[22:23], v[52:53]
	global_load_dword v52, v[18:19], off
	v_lshl_add_u64 v[18:19], v[18:19], 0, v[24:25]
	s_waitcnt vmcnt(62)
	v_cndmask_b32_e64 v28, v20, v21, s[40:41]
	v_mov_b32_e32 v55, v54
	v_cvt_f16_f32_e32 v28, v28
	v_pk_mul_f32 v[22:23], v[16:17], v[20:21] op_sel:[0,1] op_sel_hi:[1,0]
	v_permlane32_swap_b32_e32 v54, v55
	global_store_short v31, v28, s[6:7]
	v_pk_fma_f32 v[22:23], v[14:15], v[20:21], v[22:23] neg_lo:[0,0,1]
	v_add_u32_e32 v31, v31, v24
	v_pk_add_f32 v[20:21], v[22:23], v[54:55]
	global_load_dword v54, v[18:19], off
	v_lshl_add_u64 v[18:19], v[18:19], 0, v[24:25]
	s_waitcnt vmcnt(62)
	v_cndmask_b32_e64 v28, v20, v21, s[40:41]
	v_mov_b32_e32 v57, v56
	v_cvt_f16_f32_e32 v28, v28
	v_pk_mul_f32 v[22:23], v[16:17], v[20:21] op_sel:[0,1] op_sel_hi:[1,0]
	v_permlane32_swap_b32_e32 v56, v57
	global_store_short v31, v28, s[6:7]
	v_pk_fma_f32 v[22:23], v[14:15], v[20:21], v[22:23] neg_lo:[0,0,1]
	v_add_u32_e32 v31, v31, v24
	v_pk_add_f32 v[20:21], v[22:23], v[56:57]
	global_load_dword v56, v[18:19], off
	v_lshl_add_u64 v[18:19], v[18:19], 0, v[24:25]
	s_waitcnt vmcnt(62)
	v_cndmask_b32_e64 v28, v20, v21, s[40:41]
	v_mov_b32_e32 v59, v58
	v_cvt_f16_f32_e32 v28, v28
	v_pk_mul_f32 v[22:23], v[16:17], v[20:21] op_sel:[0,1] op_sel_hi:[1,0]
	v_permlane32_swap_b32_e32 v58, v59
	global_store_short v31, v28, s[6:7]
	v_pk_fma_f32 v[22:23], v[14:15], v[20:21], v[22:23] neg_lo:[0,0,1]
	v_add_u32_e32 v31, v31, v24
	v_pk_add_f32 v[20:21], v[22:23], v[58:59]
	global_load_dword v58, v[18:19], off
	v_lshl_add_u64 v[18:19], v[18:19], 0, v[24:25]
	s_waitcnt vmcnt(62)
	v_cndmask_b32_e64 v28, v20, v21, s[40:41]
	v_mov_b32_e32 v61, v60
	v_cvt_f16_f32_e32 v28, v28
	v_pk_mul_f32 v[22:23], v[16:17], v[20:21] op_sel:[0,1] op_sel_hi:[1,0]
	v_permlane32_swap_b32_e32 v60, v61
	global_store_short v31, v28, s[6:7]
	v_pk_fma_f32 v[22:23], v[14:15], v[20:21], v[22:23] neg_lo:[0,0,1]
	v_add_u32_e32 v31, v31, v24
	v_pk_add_f32 v[20:21], v[22:23], v[60:61]
	global_load_dword v60, v[18:19], off
	v_lshl_add_u64 v[18:19], v[18:19], 0, v[24:25]
	s_waitcnt vmcnt(62)
	v_cndmask_b32_e64 v28, v20, v21, s[40:41]
	v_mov_b32_e32 v63, v62
	v_cvt_f16_f32_e32 v28, v28
	v_pk_mul_f32 v[22:23], v[16:17], v[20:21] op_sel:[0,1] op_sel_hi:[1,0]
	v_permlane32_swap_b32_e32 v62, v63
	global_store_short v31, v28, s[6:7]
	v_pk_fma_f32 v[22:23], v[14:15], v[20:21], v[22:23] neg_lo:[0,0,1]
	v_add_u32_e32 v31, v31, v24
	v_pk_add_f32 v[20:21], v[22:23], v[62:63]
	global_load_dword v62, v[18:19], off
	v_lshl_add_u64 v[18:19], v[18:19], 0, v[24:25]
	s_waitcnt vmcnt(62)
	v_cndmask_b32_e64 v28, v20, v21, s[40:41]
	v_mov_b32_e32 v65, v64
	v_cvt_f16_f32_e32 v28, v28
	v_pk_mul_f32 v[22:23], v[16:17], v[20:21] op_sel:[0,1] op_sel_hi:[1,0]
	v_permlane32_swap_b32_e32 v64, v65
	global_store_short v31, v28, s[6:7]
	v_pk_fma_f32 v[22:23], v[14:15], v[20:21], v[22:23] neg_lo:[0,0,1]
	v_add_u32_e32 v31, v31, v24
	v_pk_add_f32 v[20:21], v[22:23], v[64:65]
	global_load_dword v64, v[18:19], off
	v_lshl_add_u64 v[18:19], v[18:19], 0, v[24:25]
	s_waitcnt vmcnt(62)
	v_cndmask_b32_e64 v28, v20, v21, s[40:41]
	v_mov_b32_e32 v67, v66
	v_cvt_f16_f32_e32 v28, v28
	v_pk_mul_f32 v[22:23], v[16:17], v[20:21] op_sel:[0,1] op_sel_hi:[1,0]
	v_permlane32_swap_b32_e32 v66, v67
	global_store_short v31, v28, s[6:7]
	v_pk_fma_f32 v[22:23], v[14:15], v[20:21], v[22:23] neg_lo:[0,0,1]
	v_add_u32_e32 v31, v31, v24
	v_pk_add_f32 v[20:21], v[22:23], v[66:67]
	global_load_dword v66, v[18:19], off
	v_lshl_add_u64 v[18:19], v[18:19], 0, v[24:25]
	s_waitcnt vmcnt(62)
	v_cndmask_b32_e64 v28, v20, v21, s[40:41]
	v_mov_b32_e32 v69, v68
	v_cvt_f16_f32_e32 v28, v28
	v_pk_mul_f32 v[22:23], v[16:17], v[20:21] op_sel:[0,1] op_sel_hi:[1,0]
	v_permlane32_swap_b32_e32 v68, v69
	global_store_short v31, v28, s[6:7]
	v_pk_fma_f32 v[22:23], v[14:15], v[20:21], v[22:23] neg_lo:[0,0,1]
	v_add_u32_e32 v31, v31, v24
	v_pk_add_f32 v[20:21], v[22:23], v[68:69]
	global_load_dword v68, v[18:19], off
	v_lshl_add_u64 v[18:19], v[18:19], 0, v[24:25]
	s_waitcnt vmcnt(62)
	v_cndmask_b32_e64 v28, v20, v21, s[40:41]
	v_mov_b32_e32 v71, v70
	v_cvt_f16_f32_e32 v28, v28
	v_pk_mul_f32 v[22:23], v[16:17], v[20:21] op_sel:[0,1] op_sel_hi:[1,0]
	v_permlane32_swap_b32_e32 v70, v71
	global_store_short v31, v28, s[6:7]
	v_pk_fma_f32 v[22:23], v[14:15], v[20:21], v[22:23] neg_lo:[0,0,1]
	v_add_u32_e32 v31, v31, v24
	v_pk_add_f32 v[20:21], v[22:23], v[70:71]
	global_load_dword v70, v[18:19], off
	v_lshl_add_u64 v[18:19], v[18:19], 0, v[24:25]
.LBB0_1276:
	s_or_b64 exec, exec, s[18:19]
	v_mov_b32_e32 v2, v0
	v_readlane_b32 s4, v253, 24
	s_nop 0
	v_cmp_lt_i32_e32 vcc, 63, v2
	s_waitcnt vmcnt(0)
	v_add_u32_e32 v5, s4, v2
	s_mov_b32 s4, 0x80000
	v_cmp_gt_i32_e64 s[40:41], s4, v5
	s_and_b64 s[4:5], vcc, s[40:41]
	s_and_saveexec_b64 s[16:17], s[4:5]
	s_cbranch_execz .LBB0_1281
	v_readfirstlane_b32 s4, v5
	v_mbcnt_lo_u32_b32 v6, -1, 0
	v_mbcnt_hi_u32_b32 v6, -1, v6
	v_lshlrev_b32_e32 v6, 2, v6
	v_readlane_b32 s14, v253, 18
	v_readlane_b32 s15, v253, 19
.Lgs_elem:
	v_readlane_b32 s8, v254, 42
	v_readlane_b32 s9, v254, 43
	v_readlane_b32 s12, v253, 22
	v_readlane_b32 s13, v253, 23
	s_and_b32 s5, s4, 0x7fff
	s_bfe_u32 s6, s4, 0x1000f
	s_lshr_b32 s7, s4, 16
	s_mul_i32 s7, s7, 0x42
	s_add_i32 s7, s7, s6
	s_mov_b32 s10, 0x40000
	s_mov_b32 s11, 0
	s_movk_i32 s100, 0x400
	s_mov_b32 s41, 0
	s_cmp_eq_u32 s6, 0
	s_cbranch_scc1 .Lgs_fwd
	s_mov_b32 s10, 0xfffc0000
	s_mov_b32 s11, -1
	s_mov_b32 s100, 0xfffffc00
	s_movk_i32 s41, 62
.Lgs_fwd:
	s_add_i32 s18, s7, 64
	s_lshl_b32 s19, s18, 17
	s_lshl_b32 s29, s5, 2
	s_add_u32 s19, s19, s29
	s_add_u32 s8, s8, s19
	s_addc_u32 s9, s9, 0
	s_add_u32 s12, s12, s19
	s_addc_u32 s13, s13, 0
	s_lshl_b32 s18, s18, 9
	s_lshr_b32 s29, s5, 8
	s_lshl_b32 s29, s29, 2
	s_add_u32 s18, s18, s29
	s_add_u32 s26, s14, s18
	s_addc_u32 s27, s15, 0
	s_sub_i32 s30, s41, 64
	s_lshl_b32 s30, s30, 17
	s_ashr_i32 s31, s30, 31
	s_ashr_i32 s34, s30, 8
	v_mov_b32_e32 v7, 0
	global_load_dword v10, v6, s[8:9]
	global_load_dword v21, v3, s[26:27]
	s_add_u32 s8, s8, s30
	s_addc_u32 s9, s9, s31
	s_add_u32 s26, s26, s34
	s_addc_u32 s27, s27, s31
	global_load_dword v11, v6, s[8:9]
	global_load_dword v22, v3, s[26:27]
	s_add_u32 s8, s8, s10
	s_addc_u32 s9, s9, s11
	s_add_u32 s26, s26, s100
	s_addc_u32 s27, s27, s11
	global_load_dword v12, v6, s[8:9]
	global_load_dword v23, v3, s[26:27]
	s_add_u32 s8, s8, s10
	s_addc_u32 s9, s9, s11
	s_add_u32 s26, s26, s100
	s_addc_u32 s27, s27, s11
	global_load_dword v13, v6, s[8:9]
	global_load_dword v24, v3, s[26:27]
	s_add_u32 s8, s8, s10
	s_addc_u32 s9, s9, s11
	s_add_u32 s26, s26, s100
	s_addc_u32 s27, s27, s11
	global_load_dword v14, v6, s[8:9]
	global_load_dword v25, v3, s[26:27]
	s_add_u32 s8, s8, s10
	s_addc_u32 s9, s9, s11
	s_add_u32 s26, s26, s100
	s_addc_u32 s27, s27, s11
	global_load_dword v15, v6, s[8:9]
	global_load_dword v26, v3, s[26:27]
	s_add_u32 s8, s8, s10
	s_addc_u32 s9, s9, s11
	s_add_u32 s26, s26, s100
	s_addc_u32 s27, s27, s11
	global_load_dword v16, v6, s[8:9]
	global_load_dword v27, v3, s[26:27]
	s_add_u32 s8, s8, s10
	s_addc_u32 s9, s9, s11
	s_add_u32 s26, s26, s100
	s_addc_u32 s27, s27, s11
	global_load_dword v17, v6, s[8:9]
	global_load_dword v28, v3, s[26:27]
	s_add_u32 s8, s8, s10
	s_addc_u32 s9, s9, s11
	s_add_u32 s26, s26, s100
	s_addc_u32 s27, s27, s11
	global_load_dword v18, v6, s[8:9]
	global_load_dword v29, v3, s[26:27]
	s_add_u32 s8, s8, s10
	s_addc_u32 s9, s9, s11
	s_add_u32 s26, s26, s100
	s_addc_u32 s27, s27, s11
	global_load_dword v19, v6, s[8:9]
	global_load_dword v30, v3, s[26:27]
	s_add_u32 s8, s8, s10
	s_addc_u32 s9, s9, s11
	s_add_u32 s26, s26, s100
	s_addc_u32 s27, s27, s11
	global_load_dword v20, v6, s[8:9]
	global_load_dword v31, v3, s[26:27]
	s_add_u32 s8, s8, s10
	s_addc_u32 s9, s9, s11
	s_add_u32 s26, s26, s100
	s_addc_u32 s27, s27, s11
	global_load_dword v32, v6, s[8:9]
	global_load_dword v43, v3, s[26:27]
	s_add_u32 s8, s8, s10
	s_addc_u32 s9, s9, s11
	s_add_u32 s26, s26, s100
	s_addc_u32 s27, s27, s11
	global_load_dword v33, v6, s[8:9]
	global_load_dword v44, v3, s[26:27]
	s_add_u32 s8, s8, s10
	s_addc_u32 s9, s9, s11
	s_add_u32 s26, s26, s100
	s_addc_u32 s27, s27, s11
	global_load_dword v34, v6, s[8:9]
	global_load_dword v45, v3, s[26:27]
	s_add_u32 s8, s8, s10
	s_addc_u32 s9, s9, s11
	s_add_u32 s26, s26, s100
	s_addc_u32 s27, s27, s11
	global_load_dword v35, v6, s[8:9]
	global_load_dword v46, v3, s[26:27]
	s_add_u32 s8, s8, s10
	s_addc_u32 s9, s9, s11
	s_add_u32 s26, s26, s100
	s_addc_u32 s27, s27, s11
	global_load_dword v36, v6, s[8:9]
	global_load_dword v47, v3, s[26:27]
	s_add_u32 s8, s8, s10
	s_addc_u32 s9, s9, s11
	s_add_u32 s26, s26, s100
	s_addc_u32 s27, s27, s11
	global_load_dword v37, v6, s[8:9]
	global_load_dword v48, v3, s[26:27]
	s_add_u32 s8, s8, s10
	s_addc_u32 s9, s9, s11
	s_add_u32 s26, s26, s100
	s_addc_u32 s27, s27, s11
	global_load_dword v38, v6, s[8:9]
	global_load_dword v49, v3, s[26:27]
	s_add_u32 s8, s8, s10
	s_addc_u32 s9, s9, s11
	s_add_u32 s26, s26, s100
	s_addc_u32 s27, s27, s11
	global_load_dword v39, v6, s[8:9]
	global_load_dword v50, v3, s[26:27]
	s_add_u32 s8, s8, s10
	s_addc_u32 s9, s9, s11
	s_add_u32 s26, s26, s100
	s_addc_u32 s27, s27, s11
	global_load_dword v40, v6, s[8:9]
	global_load_dword v51, v3, s[26:27]
	s_add_u32 s8, s8, s10
	s_addc_u32 s9, s9, s11
	s_add_u32 s26, s26, s100
	s_addc_u32 s27, s27, s11
	global_load_dword v41, v6, s[8:9]
	global_load_dword v52, v3, s[26:27]
	s_add_u32 s8, s8, s10
	s_addc_u32 s9, s9, s11
	s_add_u32 s26, s26, s100
	s_addc_u32 s27, s27, s11
	global_load_dword v42, v6, s[8:9]
	global_load_dword v53, v3, s[26:27]
	s_waitcnt vmcnt(42)
	global_store_dword v6, v7, s[12:13]
	v_fma_f32 v7, v21, v7, v10
	s_add_u32 s12, s12, s30
	s_addc_u32 s13, s13, s31
	s_waitcnt vmcnt(41)
	global_store_dword v6, v7, s[12:13]
	v_fma_f32 v7, v22, v7, v11
	s_add_u32 s12, s12, s10
	s_addc_u32 s13, s13, s11
	s_waitcnt vmcnt(40)
	global_store_dword v6, v7, s[12:13]
	v_fma_f32 v7, v23, v7, v12
	s_add_u32 s12, s12, s10
	s_addc_u32 s13, s13, s11
	s_waitcnt vmcnt(39)
	global_store_dword v6, v7, s[12:13]
	v_fma_f32 v7, v24, v7, v13
	s_add_u32 s12, s12, s10
	s_addc_u32 s13, s13, s11
	s_waitcnt vmcnt(38)
	global_store_dword v6, v7, s[12:13]
	v_fma_f32 v7, v25, v7, v14
	s_add_u32 s12, s12, s10
	s_addc_u32 s13, s13, s11
	s_waitcnt vmcnt(37)
	global_store_dword v6, v7, s[12:13]
	v_fma_f32 v7, v26, v7, v15
	s_add_u32 s12, s12, s10
	s_addc_u32 s13, s13, s11
	s_waitcnt vmcnt(36)
	global_store_dword v6, v7, s[12:13]
	v_fma_f32 v7, v27, v7, v16
	s_add_u32 s12, s12, s10
	s_addc_u32 s13, s13, s11
	s_waitcnt vmcnt(35)
	global_store_dword v6, v7, s[12:13]
	v_fma_f32 v7, v28, v7, v17
	s_add_u32 s12, s12, s10
	s_addc_u32 s13, s13, s11
	s_waitcnt vmcnt(34)
	global_store_dword v6, v7, s[12:13]
	v_fma_f32 v7, v29, v7, v18
	s_add_u32 s12, s12, s10
	s_addc_u32 s13, s13, s11
	s_waitcnt vmcnt(33)
	global_store_dword v6, v7, s[12:13]
	v_fma_f32 v7, v30, v7, v19
	s_add_u32 s12, s12, s10
	s_addc_u32 s13, s13, s11
	s_waitcnt vmcnt(32)
	global_store_dword v6, v7, s[12:13]
	v_fma_f32 v7, v31, v7, v20
	s_add_u32 s8, s8, s10
	s_addc_u32 s9, s9, s11
	s_add_u32 s26, s26, s100
	s_addc_u32 s27, s27, s11
	global_load_dword v10, v6, s[8:9]
	global_load_dword v21, v3, s[26:27]
	s_add_u32 s8, s8, s10
	s_addc_u32 s9, s9, s11
	s_add_u32 s26, s26, s100
	s_addc_u32 s27, s27, s11
	global_load_dword v11, v6, s[8:9]
	global_load_dword v22, v3, s[26:27]
	s_add_u32 s8, s8, s10
	s_addc_u32 s9, s9, s11
	s_add_u32 s26, s26, s100
	s_addc_u32 s27, s27, s11
	global_load_dword v12, v6, s[8:9]
	global_load_dword v23, v3, s[26:27]
	s_add_u32 s8, s8, s10
	s_addc_u32 s9, s9, s11
	s_add_u32 s26, s26, s100
	s_addc_u32 s27, s27, s11
	global_load_dword v13, v6, s[8:9]
	global_load_dword v24, v3, s[26:27]
	s_add_u32 s8, s8, s10
	s_addc_u32 s9, s9, s11
	s_add_u32 s26, s26, s100
	s_addc_u32 s27, s27, s11
	global_load_dword v14, v6, s[8:9]
	global_load_dword v25, v3, s[26:27]
	s_add_u32 s8, s8, s10
	s_addc_u32 s9, s9, s11
	s_add_u32 s26, s26, s100
	s_addc_u32 s27, s27, s11
	global_load_dword v15, v6, s[8:9]
	global_load_dword v26, v3, s[26:27]
	s_add_u32 s8, s8, s10
	s_addc_u32 s9, s9, s11
	s_add_u32 s26, s26, s100
	s_addc_u32 s27, s27, s11
	global_load_dword v16, v6, s[8:9]
	global_load_dword v27, v3, s[26:27]
	s_add_u32 s8, s8, s10
	s_addc_u32 s9, s9, s11
	s_add_u32 s26, s26, s100
	s_addc_u32 s27, s27, s11
	global_load_dword v17, v6, s[8:9]
	global_load_dword v28, v3, s[26:27]
	s_add_u32 s8, s8, s10
	s_addc_u32 s9, s9, s11
	s_add_u32 s26, s26, s100
	s_addc_u32 s27, s27, s11
	global_load_dword v18, v6, s[8:9]
	global_load_dword v29, v3, s[26:27]
	s_add_u32 s8, s8, s10
	s_addc_u32 s9, s9, s11
	s_add_u32 s26, s26, s100
	s_addc_u32 s27, s27, s11
	global_load_dword v19, v6, s[8:9]
	global_load_dword v30, v3, s[26:27]
	s_add_u32 s8, s8, s10
	s_addc_u32 s9, s9, s11
	s_add_u32 s26, s26, s100
	s_addc_u32 s27, s27, s11
	global_load_dword v20, v6, s[8:9]
	global_load_dword v31, v3, s[26:27]
	s_add_u32 s12, s12, s10
	s_addc_u32 s13, s13, s11
	s_waitcnt vmcnt(53)
	global_store_dword v6, v7, s[12:13]
	v_fma_f32 v7, v43, v7, v32
	s_add_u32 s12, s12, s10
	s_addc_u32 s13, s13, s11
	s_waitcnt vmcnt(52)
	global_store_dword v6, v7, s[12:13]
	v_fma_f32 v7, v44, v7, v33
	s_add_u32 s12, s12, s10
	s_addc_u32 s13, s13, s11
	s_waitcnt vmcnt(51)
	global_store_dword v6, v7, s[12:13]
	v_fma_f32 v7, v45, v7, v34
	s_add_u32 s12, s12, s10
	s_addc_u32 s13, s13, s11
	s_waitcnt vmcnt(50)
	global_store_dword v6, v7, s[12:13]
	v_fma_f32 v7, v46, v7, v35
	s_add_u32 s12, s12, s10
	s_addc_u32 s13, s13, s11
	s_waitcnt vmcnt(49)
	global_store_dword v6, v7, s[12:13]
	v_fma_f32 v7, v47, v7, v36
	s_add_u32 s12, s12, s10
	s_addc_u32 s13, s13, s11
	s_waitcnt vmcnt(48)
	global_store_dword v6, v7, s[12:13]
	v_fma_f32 v7, v48, v7, v37
	s_add_u32 s12, s12, s10
	s_addc_u32 s13, s13, s11
	s_waitcnt vmcnt(47)
	global_store_dword v6, v7, s[12:13]
	v_fma_f32 v7, v49, v7, v38
	s_add_u32 s12, s12, s10
	s_addc_u32 s13, s13, s11
	s_waitcnt vmcnt(46)
	global_store_dword v6, v7, s[12:13]
	v_fma_f32 v7, v50, v7, v39
	s_add_u32 s12, s12, s10
	s_addc_u32 s13, s13, s11
	s_waitcnt vmcnt(45)
	global_store_dword v6, v7, s[12:13]
	v_fma_f32 v7, v51, v7, v40
	s_add_u32 s12, s12, s10
	s_addc_u32 s13, s13, s11
	s_waitcnt vmcnt(44)
	global_store_dword v6, v7, s[12:13]
	v_fma_f32 v7, v52, v7, v41
	s_add_u32 s12, s12, s10
	s_addc_u32 s13, s13, s11
	s_waitcnt vmcnt(43)
	global_store_dword v6, v7, s[12:13]
	v_fma_f32 v7, v53, v7, v42
	s_add_u32 s12, s12, s10
	s_addc_u32 s13, s13, s11
	s_waitcnt vmcnt(31)
	global_store_dword v6, v7, s[12:13]
	v_fma_f32 v7, v21, v7, v10
	s_add_u32 s12, s12, s10
	s_addc_u32 s13, s13, s11
	s_waitcnt vmcnt(30)
	global_store_dword v6, v7, s[12:13]
	v_fma_f32 v7, v22, v7, v11
	s_add_u32 s12, s12, s10
	s_addc_u32 s13, s13, s11
	s_waitcnt vmcnt(29)
	global_store_dword v6, v7, s[12:13]
	v_fma_f32 v7, v23, v7, v12
	s_add_u32 s12, s12, s10
	s_addc_u32 s13, s13, s11
	s_waitcnt vmcnt(28)
	global_store_dword v6, v7, s[12:13]
	v_fma_f32 v7, v24, v7, v13
	s_add_u32 s12, s12, s10
	s_addc_u32 s13, s13, s11
	s_waitcnt vmcnt(27)
	global_store_dword v6, v7, s[12:13]
	v_fma_f32 v7, v25, v7, v14
	s_add_u32 s12, s12, s10
	s_addc_u32 s13, s13, s11
	s_waitcnt vmcnt(26)
	global_store_dword v6, v7, s[12:13]
	v_fma_f32 v7, v26, v7, v15
	s_add_u32 s12, s12, s10
	s_addc_u32 s13, s13, s11
	s_waitcnt vmcnt(25)
	global_store_dword v6, v7, s[12:13]
	v_fma_f32 v7, v27, v7, v16
	s_add_u32 s12, s12, s10
	s_addc_u32 s13, s13, s11
	s_waitcnt vmcnt(24)
	global_store_dword v6, v7, s[12:13]
	v_fma_f32 v7, v28, v7, v17
	s_add_u32 s12, s12, s10
	s_addc_u32 s13, s13, s11
	s_waitcnt vmcnt(23)
	global_store_dword v6, v7, s[12:13]
	v_fma_f32 v7, v29, v7, v18
	s_add_u32 s12, s12, s10
	s_addc_u32 s13, s13, s11
	s_waitcnt vmcnt(22)
	global_store_dword v6, v7, s[12:13]
	v_fma_f32 v7, v30, v7, v19
	s_add_u32 s12, s12, s10
	s_addc_u32 s13, s13, s11
	s_waitcnt vmcnt(21)
	global_store_dword v6, v7, s[12:13]
	v_fma_f32 v7, v31, v7, v20
	s_add_u32 s4, s4, 0x1c000
	s_cmp_lt_u32 s4, 0x80000
	s_cbranch_scc1 .Lgs_elem

	.amdhsa_kernel _Z6mk_fwd4Args
		.amdhsa_group_segment_fixed_size 0
		.amdhsa_private_segment_fixed_size 0
		.amdhsa_kernarg_size 600
		.amdhsa_user_sgpr_count 2
		.amdhsa_user_sgpr_dispatch_ptr 0
		.amdhsa_user_sgpr_queue_ptr 0
		.amdhsa_user_sgpr_kernarg_segment_ptr 1
		.amdhsa_user_sgpr_dispatch_id 0
		.amdhsa_user_sgpr_kernarg_preload_length 0
		.amdhsa_user_sgpr_kernarg_preload_offset 0
		.amdhsa_user_sgpr_private_segment_size 0
		.amdhsa_uses_dynamic_stack 0
		.amdhsa_enable_private_segment 0
		.amdhsa_system_sgpr_workgroup_id_x 1
		.amdhsa_system_sgpr_workgroup_id_y 0
		.amdhsa_system_sgpr_workgroup_id_z 0
		.amdhsa_system_sgpr_workgroup_info 0
		.amdhsa_system_vgpr_workitem_id 0
		.amdhsa_next_free_vgpr 256
		.amdhsa_next_free_sgpr 102
		.amdhsa_accum_offset 256
		.amdhsa_reserve_vcc 1
		.amdhsa_float_round_mode_32 0
		.amdhsa_float_round_mode_16_64 0
		.amdhsa_float_denorm_mode_32 3
		.amdhsa_float_denorm_mode_16_64 3
		.amdhsa_dx10_clamp 1
		.amdhsa_ieee_mode 1
		.amdhsa_fp16_overflow 0
		.amdhsa_tg_split 0
		.amdhsa_exception_fp_ieee_invalid_op 0
		.amdhsa_exception_fp_denorm_src 0
		.amdhsa_exception_fp_ieee_div_zero 0
		.amdhsa_exception_fp_ieee_overflow 0
		.amdhsa_exception_fp_ieee_underflow 0
		.amdhsa_exception_fp_ieee_inexact 0
		.amdhsa_exception_int_div_zero 0
	.end_amdhsa_kernel

amdhsa.kernels:
  - .agpr_count:     0
    .args:
      - .offset:         0
        .size:           344
        .value_kind:     by_value
      - .offset:         344
        .size:           4
        .value_kind:     hidden_block_count_x
      - .offset:         348
        .size:           4
        .value_kind:     hidden_block_count_y
      - .offset:         352
        .size:           4
        .value_kind:     hidden_block_count_z
      - .offset:         356
        .size:           2
        .value_kind:     hidden_group_size_x
      - .offset:         358
        .size:           2
        .value_kind:     hidden_group_size_y
      - .offset:         360
        .size:           2
        .value_kind:     hidden_group_size_z
      - .offset:         362
        .size:           2
        .value_kind:     hidden_remainder_x
      - .offset:         364
        .size:           2
        .value_kind:     hidden_remainder_y
      - .offset:         366
        .size:           2
        .value_kind:     hidden_remainder_z
      - .offset:         384
        .size:           8
        .value_kind:     hidden_global_offset_x
      - .offset:         392
        .size:           8
        .value_kind:     hidden_global_offset_y
      - .offset:         400
        .size:           8
        .value_kind:     hidden_global_offset_z
      - .offset:         408
        .size:           2
        .value_kind:     hidden_grid_dims
      - .offset:         464
        .size:           4
        .value_kind:     hidden_dynamic_lds_size
    .group_segment_fixed_size: 0
    .kernarg_segment_align: 8
    .kernarg_segment_size: 600
    .language:       OpenCL C
    .language_version:
      - 2
      - 0
    .max_flat_workgroup_size: 512
    .name:           _Z6mk_fwd4Args
    .private_segment_fixed_size: 0
    .sgpr_count:     108
    .sgpr_spill_count: 386
    .symbol:         _Z6mk_fwd4Args.kd
    .uniform_work_group_size: 1
    .uses_dynamic_stack: false
    .vgpr_count:     256
    .vgpr_spill_count: 0
    .wavefront_size: 64
